# baseline (speedup 1.0000x reference)
; #define WAIT_V(n) asm volatile("s_waitcnt vmcnt(" #n ")" ::: "memory")
; #define BAR __builtin_amdgcn_s_barrier()
; __device__ __forceinline__ void gemm_tile(const bf16_t* __restrict__ A, const bf16_t* __restrict__ Bt, int K, int brow, int bcol,
;                                           int mode, const Params& p, char* wsb, const float* xg, float* outg, int S, char* shmc) {
;     ...
;   f32x4 acc[2][2][4][2] = {};
;     ...
;   if (need_stats) {
;     float s1 = 0.f, s2 = 0.f;
; #pragma unroll
;     for (int i = 0; i < 8; ++i) { s1 += stv[i][0] + stv[i][2]; s2 += stv[i][1] + stv[i][3]; }
;     const float mu = s1 * (1.f / 2048.f), var = fmaxf(s2 * (1.f / 2048.f) - mu * mu, 0.f);
;     rst[tidl * 2] = mu; rst[tidl * 2 + 1] = rsqrtf(var + 1e-5f);
;   }
;   STAGE(SB(1, 0), Bt, 0, bcol, 1); STAGE(SA(1, 0), A, 0, brow, 1); STAGE(SB(1, 1), Bt, 0, bcol + HALF, 1);
;   WAIT_V(6); BAR;
;   for (int t = 0; t < nt - 2; t += 2) {
.LBB0_168:
	s_or_b64 exec, exec, s[20:21]
	s_add_u32 s14, s4, 0x80
	v_readlane_b32 s21, v249, 32
	s_addc_u32 s15, s5, 0
	s_add_i32 s20, s21, s42
	s_mov_b32 m0, s20
	s_waitcnt vmcnt(0) lgkmcnt(0)
	v_and_b32_e32 v0, 15, v162
	global_load_lds_dwordx4 v128, s[14:15]
	s_add_i32 m0, s20, 0x2000
	v_lshlrev_b32_e32 v3, 2, v162
	global_load_lds_dwordx4 v129, s[14:15]
	s_add_u32 s14, s18, 0x80
	s_addc_u32 s15, s19, 0
	s_add_i32 s18, s22, 0x8000
	s_mov_b32 m0, s18
	s_add_i32 s19, s22, 0xa000
	v_and_b32_e32 v1, 48, v162
	global_load_lds_dwordx4 v128, s[14:15]
	s_mov_b32 m0, s19
	v_lshlrev_b32_e32 v0, 6, v0
	global_load_lds_dwordx4 v129, s[14:15]
	s_add_u32 s14, s16, 0x80
	s_addc_u32 s15, s17, 0
	v_readlane_b32 s17, v249, 33
	s_add_i32 s16, s17, s42
	s_mov_b32 m0, s16
	v_and_b32_e32 v3, 32, v3
	global_load_lds_dwordx4 v128, s[14:15]
	s_add_i32 m0, s16, 0x2000
	v_bitop3_b32 v0, v0, v3, v1 bitop3:0x36
	global_load_lds_dwordx4 v129, s[14:15]
	s_add_i32 s14, 0, 0x10000
	v_add_u32_e32 v4, s14, v0
	s_add_i32 s14, 0, 0x14000
	s_add_u32 s16, s62, s36
	v_add_u32_e32 v7, s17, v0
	s_addc_u32 s17, s63, s37
	v_add_u32_e32 v5, s14, v0
	v_add_u32_e32 v6, s21, v0
	v_add_u32_e32 v9, 0, v0
	v_lshlrev_b32_e32 v0, 6, v162
	s_movk_i32 s14, 0x3c0
	s_add_u32 s20, s60, s6
	s_waitcnt vmcnt(6)
	v_lshlrev_b32_e32 v2, 12, v32
	v_lshlrev_b32_e32 v8, 13, v33
	v_and_or_b32 v0, v0, s14, v1
	s_addc_u32 s21, s61, s7
	v_and_b32_e32 v2, 0x3000, v2
	v_xad_u32 v1, v0, v3, 0
	v_or_b32_e32 v3, 0x800, v8
	v_or_b32_e32 v10, 0x1000, v8
	v_or_b32_e32 v11, 0x1800, v8
	s_add_u32 s42, s60, s10
	v_mov_b32_e32 v0, 0
	s_addc_u32 s43, s61, s11
	s_mov_b32 s44, 0
	s_mov_b64 s[14:15], 0
	v_add_u32_e32 v133, v4, v2
	v_add_u32_e32 v171, v9, v8
	v_add_u32_e32 v170, v1, v3
	v_add_u32_e32 v169, v1, v10
	v_add_u32_e32 v167, v1, v11
	v_add_u32_e32 v132, v5, v2
	v_add_u32_e32 v131, v6, v2
	v_add_u32_e32 v130, v7, v2
	v_mov_b32_e32 v1, v0
	v_mov_b32_e32 v2, v0
	v_mov_b32_e32 v3, v0
	v_mov_b32_e32 v4, v0
	v_mov_b32_e32 v5, v0
	v_mov_b32_e32 v6, v0
	v_mov_b32_e32 v7, v0
	v_mov_b32_e32 v8, v0
	v_mov_b32_e32 v9, v0
	v_mov_b32_e32 v10, v0
	v_mov_b32_e32 v11, v0
	v_mov_b32_e32 v12, v0
	v_mov_b32_e32 v13, v0
	v_mov_b32_e32 v14, v0
	v_mov_b32_e32 v15, v0
	v_mov_b32_e32 v16, v0
	v_mov_b32_e32 v17, v0
	v_mov_b32_e32 v18, v0
	v_mov_b32_e32 v19, v0
	v_mov_b32_e32 v20, v0
	v_mov_b32_e32 v21, v0
	v_mov_b32_e32 v22, v0
	v_mov_b32_e32 v23, v0
	v_mov_b32_e32 v24, v0
	v_mov_b32_e32 v25, v0
	v_mov_b32_e32 v26, v0
	v_mov_b32_e32 v27, v0
	v_mov_b32_e32 v28, v0
	v_mov_b32_e32 v29, v0
	v_mov_b32_e32 v30, v0
	v_mov_b32_e32 v31, v0
	v_mov_b32_e32 v32, v0
	v_mov_b32_e32 v33, v0
	v_mov_b32_e32 v34, v0
	v_mov_b32_e32 v35, v0
	v_mov_b32_e32 v36, v0
	v_mov_b32_e32 v37, v0
	v_mov_b32_e32 v38, v0
	v_mov_b32_e32 v39, v0
	v_mov_b32_e32 v40, v0
	v_mov_b32_e32 v41, v0
	v_mov_b32_e32 v42, v0
	v_mov_b32_e32 v43, v0
	v_mov_b32_e32 v44, v0
	v_mov_b32_e32 v45, v0
	v_mov_b32_e32 v46, v0
	v_mov_b32_e32 v47, v0
	v_mov_b32_e32 v48, v0
	v_mov_b32_e32 v49, v0
	v_mov_b32_e32 v50, v0
	v_mov_b32_e32 v51, v0
	v_mov_b32_e32 v52, v0
	v_mov_b32_e32 v53, v0
	v_mov_b32_e32 v54, v0
	v_mov_b32_e32 v55, v0
	v_mov_b32_e32 v56, v0
	v_mov_b32_e32 v57, v0
	v_mov_b32_e32 v58, v0
	v_mov_b32_e32 v59, v0
	v_mov_b32_e32 v60, v0
	v_mov_b32_e32 v61, v0
	v_mov_b32_e32 v62, v0
	v_mov_b32_e32 v63, v0
	v_mov_b32_e32 v64, v0
	v_mov_b32_e32 v65, v0
	v_mov_b32_e32 v66, v0
	v_mov_b32_e32 v67, v0
	v_mov_b32_e32 v68, v0
	v_mov_b32_e32 v69, v0
	v_mov_b32_e32 v70, v0
	v_mov_b32_e32 v71, v0
	v_mov_b32_e32 v72, v0
	v_mov_b32_e32 v73, v0
	v_mov_b32_e32 v74, v0
	v_mov_b32_e32 v75, v0
	v_mov_b32_e32 v76, v0
	v_mov_b32_e32 v77, v0
	v_mov_b32_e32 v78, v0
	v_mov_b32_e32 v79, v0
	v_mov_b32_e32 v80, v0
	v_mov_b32_e32 v81, v0
	v_mov_b32_e32 v82, v0
	v_mov_b32_e32 v83, v0
	v_mov_b32_e32 v84, v0
	v_mov_b32_e32 v85, v0
	v_mov_b32_e32 v86, v0
	v_mov_b32_e32 v87, v0
	v_mov_b32_e32 v88, v0
	v_mov_b32_e32 v89, v0
	v_mov_b32_e32 v90, v0
	v_mov_b32_e32 v91, v0
	v_mov_b32_e32 v92, v0
	v_mov_b32_e32 v93, v0
	v_mov_b32_e32 v94, v0
	v_mov_b32_e32 v95, v0
	v_mov_b32_e32 v96, v0
	v_mov_b32_e32 v97, v0
	v_mov_b32_e32 v98, v0
	v_mov_b32_e32 v99, v0
	v_mov_b32_e32 v100, v0
	v_mov_b32_e32 v101, v0
	v_mov_b32_e32 v102, v0
	v_mov_b32_e32 v103, v0
	v_mov_b32_e32 v104, v0
	v_mov_b32_e32 v105, v0
	v_mov_b32_e32 v106, v0
	v_mov_b32_e32 v107, v0
	v_mov_b32_e32 v108, v0
	v_mov_b32_e32 v109, v0
	v_mov_b32_e32 v110, v0
	v_mov_b32_e32 v111, v0
	v_mov_b32_e32 v112, v0
	v_mov_b32_e32 v113, v0
	v_mov_b32_e32 v114, v0
	v_mov_b32_e32 v115, v0
	v_mov_b32_e32 v116, v0
	v_mov_b32_e32 v117, v0
	v_mov_b32_e32 v118, v0
	v_mov_b32_e32 v119, v0
	v_mov_b32_e32 v120, v0
	v_mov_b32_e32 v121, v0
	v_mov_b32_e32 v122, v0
	v_mov_b32_e32 v123, v0
	v_mov_b32_e32 v124, v0
	v_mov_b32_e32 v125, v0
	v_mov_b32_e32 v126, v0
	v_mov_b32_e32 v127, v0
	s_barrier
	s_cmp_lg_u32 s100, 0
	s_cbranch_scc1 .Lgm_y
; #define LDA(dst, b, h) for (int m = 0; m < 4; ++m) for (int k = 0; k < 2; ++k) \
;     dst[m][k] = *reinterpret_cast<const bf16x8*>((char*)SA(b, h) + lds_byte(wr * 64 + m * 16 + fr, k * 32 + fq * 8))
; #define LDB(dst, b, h) for (int n = 0; n < 2; ++n) for (int k = 0; k < 2; ++k) \
;     dst[n][k] = *reinterpret_cast<const bf16x8*>((char*)SB(b, h) + lds_byte(wc * 32 + n * 16 + fr, k * 32 + fq * 8))
; #define MMA(ai, bj, At, Bt_) do { __builtin_amdgcn_s_setprio(1); \
;     for (int m = 0; m < 4; ++m) for (int n = 0; n < 2; ++n) for (int k = 0; k < 2; ++k) \
;       acc[ai][bj][m][n] = __builtin_amdgcn_mfma_f32_16x16x32_bf16(At[m][k], Bt_[n][k], acc[ai][bj][m][n], 0, 0, 0); \
;     __builtin_amdgcn_s_setprio(0); } while (0)
; #define WAIT_V(n) asm volatile("s_waitcnt vmcnt(" #n ")" ::: "memory")
; #define WAIT_L(n) asm volatile("s_waitcnt lgkmcnt(" #n ")" ::: "memory")
; #define BAR __builtin_amdgcn_s_barrier()
; #define SCHED __builtin_amdgcn_sched_barrier(0)
; __device__ __forceinline__ void gemm_tile(const bf16_t* __restrict__ A, const bf16_t* __restrict__ Bt, int K, int brow, int bcol,
;                                           int mode, const Params& p, char* wsb, const float* xg, float* outg, int S, char* shmc) {
;     ...
;   for (int t = 0; t < nt - 2; t += 2) {
;     LDB(B0, 0, 0); SCHED; LDA(At, 0, 0); STAGE(SA(1, 1), A, 0, brow + HALF, t + 1);
;     WAIT_L(8); BAR; WAIT_L(0); MMA(0, 0, At, B0); BAR; SCHED;
;     LDB(B1, 0, 1); STAGE(SB(0, 0), Bt, 0, bcol, t + 2);
;     BAR; WAIT_L(0); MMA(0, 1, At, B1); BAR;
;     LDA(At, 0, 1); STAGE(SA(0, 0), A, 0, brow, t + 2);
;     BAR; WAIT_L(0); MMA(1, 0, At, B0); BAR; SCHED;
;     STAGE(SB(0, 1), Bt, 0, bcol + HALF, t + 2);
;     WAIT_V(6); BAR; MMA(1, 1, At, B1); BAR;
.LBB0_169:
	ds_read_b128 v[134:137], v133
	ds_read_b128 v[138:141], v133 offset:1024
	ds_read_b128 v[142:145], v133 offset:2048
	ds_read_b128 v[146:149], v133 offset:3072
	s_add_u32 vcc_lo, s42, s14
	s_addc_u32 vcc_hi, s43, s15
	s_add_u32 s68, vcc_lo, 0x80
	s_addc_u32 s69, vcc_hi, 0
	s_add_i32 s98, s22, 0xc000
	s_mov_b32 m0, s98
	s_add_i32 s99, s22, 0xe000
	ds_read_b128 v[150:153], v171
	ds_read_b128 v[154:157], v171 offset:1024
	ds_read_b128 v[188:191], v170
	ds_read_b128 v[192:195], v170 offset:1024
	ds_read_b128 v[196:199], v169
	ds_read_b128 v[200:203], v169 offset:1024
	ds_read_b128 v[204:207], v167
	ds_read_b128 v[208:211], v167 offset:1024
	s_nop 0
	global_load_lds_dwordx4 v128, s[68:69]
	s_mov_b32 m0, s99
	s_nop 0
	global_load_lds_dwordx4 v129, s[68:69]
	s_waitcnt lgkmcnt(8)
	s_barrier
	s_waitcnt lgkmcnt(0)
	s_setprio 1
	s_waitcnt lgkmcnt(0)
	v_mfma_f32_16x16x32_bf16 v[124:127], v[150:153], v[134:137], v[124:127]
	v_mfma_f32_16x16x32_bf16 v[120:123], v[150:153], v[142:145], v[120:123]
	v_mfma_f32_16x16x32_bf16 v[116:119], v[188:191], v[134:137], v[116:119]
	v_mfma_f32_16x16x32_bf16 v[112:115], v[188:191], v[142:145], v[112:115]
	v_mfma_f32_16x16x32_bf16 v[108:111], v[196:199], v[134:137], v[108:111]
	v_mfma_f32_16x16x32_bf16 v[104:107], v[196:199], v[142:145], v[104:107]
	v_mfma_f32_16x16x32_bf16 v[100:103], v[204:207], v[134:137], v[100:103]
	v_mfma_f32_16x16x32_bf16 v[96:99], v[204:207], v[142:145], v[96:99]
	v_mfma_f32_16x16x32_bf16 v[124:127], v[154:157], v[138:141], v[124:127]
	v_mfma_f32_16x16x32_bf16 v[120:123], v[154:157], v[146:149], v[120:123]
	v_mfma_f32_16x16x32_bf16 v[116:119], v[192:195], v[138:141], v[116:119]
	v_mfma_f32_16x16x32_bf16 v[112:115], v[192:195], v[146:149], v[112:115]
	v_mfma_f32_16x16x32_bf16 v[108:111], v[200:203], v[138:141], v[108:111]
	v_mfma_f32_16x16x32_bf16 v[104:107], v[200:203], v[146:149], v[104:107]
	v_mfma_f32_16x16x32_bf16 v[100:103], v[208:211], v[138:141], v[100:103]
	v_mfma_f32_16x16x32_bf16 v[96:99], v[208:211], v[146:149], v[96:99]
	s_setprio 0
	s_barrier
	s_add_i32 s44, s44, 2
	s_add_u32 s51, s4, s14
	s_addc_u32 s72, s5, s15
	s_add_u32 s68, s51, 0x100
	s_addc_u32 s69, s72, 0
	s_mov_b32 m0, s23
	ds_read_b128 v[212:215], v132
	ds_read_b128 v[216:219], v132 offset:1024
	ds_read_b128 v[220:223], v132 offset:2048
	ds_read_b128 v[224:227], v132 offset:3072
	s_nop 0
	global_load_lds_dwordx4 v128, s[68:69]
	s_mov_b32 m0, s24
	s_nop 0
	global_load_lds_dwordx4 v129, s[68:69]
	s_barrier
	s_waitcnt lgkmcnt(0)
	s_setprio 1
	s_waitcnt lgkmcnt(0)
	v_mfma_f32_16x16x32_bf16 v[92:95], v[150:153], v[212:215], v[92:95]
	v_mfma_f32_16x16x32_bf16 v[88:91], v[150:153], v[220:223], v[88:91]
	v_mfma_f32_16x16x32_bf16 v[84:87], v[188:191], v[212:215], v[84:87]
	v_mfma_f32_16x16x32_bf16 v[80:83], v[188:191], v[220:223], v[80:83]
	v_mfma_f32_16x16x32_bf16 v[76:79], v[196:199], v[212:215], v[76:79]
	v_mfma_f32_16x16x32_bf16 v[72:75], v[196:199], v[220:223], v[72:75]
	v_mfma_f32_16x16x32_bf16 v[68:71], v[204:207], v[212:215], v[68:71]
	v_mfma_f32_16x16x32_bf16 v[64:67], v[204:207], v[220:223], v[64:67]
	v_mfma_f32_16x16x32_bf16 v[92:95], v[154:157], v[216:219], v[92:95]
	v_mfma_f32_16x16x32_bf16 v[88:91], v[154:157], v[224:227], v[88:91]
	v_mfma_f32_16x16x32_bf16 v[84:87], v[192:195], v[216:219], v[84:87]
	v_mfma_f32_16x16x32_bf16 v[80:83], v[192:195], v[224:227], v[80:83]
	v_mfma_f32_16x16x32_bf16 v[76:79], v[200:203], v[216:219], v[76:79]
	v_mfma_f32_16x16x32_bf16 v[72:75], v[200:203], v[224:227], v[72:75]
	v_mfma_f32_16x16x32_bf16 v[68:71], v[208:211], v[216:219], v[68:71]
	v_mfma_f32_16x16x32_bf16 v[64:67], v[208:211], v[224:227], v[64:67]
	s_setprio 0
	s_add_u32 s73, s20, s14
	s_addc_u32 s78, s21, s15
	s_add_u32 s68, s73, 0x100
	s_addc_u32 s69, s78, 0
	s_mov_b32 m0, s22
	s_barrier
	ds_read_b128 v[150:153], v171 offset:16384
	ds_read_b128 v[154:157], v171 offset:17408
	ds_read_b128 v[188:191], v170 offset:16384
	ds_read_b128 v[192:195], v170 offset:17408
	ds_read_b128 v[196:199], v169 offset:16384
	ds_read_b128 v[200:203], v169 offset:17408
	ds_read_b128 v[204:207], v167 offset:16384
	ds_read_b128 v[208:211], v167 offset:17408
	s_nop 0
	global_load_lds_dwordx4 v128, s[68:69]
	s_mov_b32 m0, s25
	s_nop 0
	global_load_lds_dwordx4 v129, s[68:69]
	s_barrier
	s_waitcnt lgkmcnt(0)
	s_setprio 1
	s_waitcnt lgkmcnt(0)
	v_mfma_f32_16x16x32_bf16 v[60:63], v[150:153], v[134:137], v[60:63]
	v_mfma_f32_16x16x32_bf16 v[56:59], v[150:153], v[142:145], v[56:59]
	v_mfma_f32_16x16x32_bf16 v[52:55], v[188:191], v[134:137], v[52:55]
	v_mfma_f32_16x16x32_bf16 v[48:51], v[188:191], v[142:145], v[48:51]
	v_mfma_f32_16x16x32_bf16 v[44:47], v[196:199], v[134:137], v[44:47]
	v_mfma_f32_16x16x32_bf16 v[40:43], v[196:199], v[142:145], v[40:43]
	v_mfma_f32_16x16x32_bf16 v[36:39], v[204:207], v[134:137], v[36:39]
	v_mfma_f32_16x16x32_bf16 v[32:35], v[204:207], v[142:145], v[32:35]
	v_mfma_f32_16x16x32_bf16 v[60:63], v[154:157], v[138:141], v[60:63]
	v_mfma_f32_16x16x32_bf16 v[56:59], v[154:157], v[146:149], v[56:59]
	v_mfma_f32_16x16x32_bf16 v[52:55], v[192:195], v[138:141], v[52:55]
	v_mfma_f32_16x16x32_bf16 v[48:51], v[192:195], v[146:149], v[48:51]
	v_mfma_f32_16x16x32_bf16 v[44:47], v[200:203], v[138:141], v[44:47]
	v_mfma_f32_16x16x32_bf16 v[40:43], v[200:203], v[146:149], v[40:43]
	v_mfma_f32_16x16x32_bf16 v[36:39], v[208:211], v[138:141], v[36:39]
	v_mfma_f32_16x16x32_bf16 v[32:35], v[208:211], v[146:149], v[32:35]
	s_setprio 0
	s_barrier
	s_add_u32 s79, s16, s14
	s_addc_u32 s80, s17, s15
	s_add_u32 s68, s79, 0x100
	s_addc_u32 s69, s80, 0
	s_mov_b32 m0, s26
	s_nop 0
	global_load_lds_dwordx4 v128, s[68:69]
	s_mov_b32 m0, s27
	s_nop 0
	global_load_lds_dwordx4 v129, s[68:69]
	s_waitcnt vmcnt(6)
	s_barrier
; #define LDA(dst, b, h) for (int m = 0; m < 4; ++m) for (int k = 0; k < 2; ++k) \
;     dst[m][k] = *reinterpret_cast<const bf16x8*>((char*)SA(b, h) + lds_byte(wr * 64 + m * 16 + fr, k * 32 + fq * 8))
; #define LDB(dst, b, h) for (int n = 0; n < 2; ++n) for (int k = 0; k < 2; ++k) \
;     dst[n][k] = *reinterpret_cast<const bf16x8*>((char*)SB(b, h) + lds_byte(wc * 32 + n * 16 + fr, k * 32 + fq * 8))
; #define MMA(ai, bj, At, Bt_) do { __builtin_amdgcn_s_setprio(1); \
;     for (int m = 0; m < 4; ++m) for (int n = 0; n < 2; ++n) for (int k = 0; k < 2; ++k) \
;       acc[ai][bj][m][n] = __builtin_amdgcn_mfma_f32_16x16x32_bf16(At[m][k], Bt_[n][k], acc[ai][bj][m][n], 0, 0, 0); \
;     __builtin_amdgcn_s_setprio(0); } while (0)
; #define WAIT_V(n) asm volatile("s_waitcnt vmcnt(" #n ")" ::: "memory")
; #define WAIT_L(n) asm volatile("s_waitcnt lgkmcnt(" #n ")" ::: "memory")
; #define BAR __builtin_amdgcn_s_barrier()
; #define SCHED __builtin_amdgcn_sched_barrier(0)
; __device__ __forceinline__ void gemm_tile(const bf16_t* __restrict__ A, const bf16_t* __restrict__ Bt, int K, int brow, int bcol,
;                                           int mode, const Params& p, char* wsb, const float* xg, float* outg, int S, char* shmc) {
;     ...
;     WAIT_V(6); BAR; MMA(1, 1, At, B1); BAR;
;     LDB(B0, 1, 0); SCHED; LDA(At, 1, 0); STAGE(SA(0, 1), A, 0, brow + HALF, t + 2);
;     WAIT_L(8); BAR; WAIT_L(0); MMA(0, 0, At, B0); BAR; SCHED;
;     LDB(B1, 1, 1); STAGE(SB(1, 0), Bt, 0, bcol, t + 3);
;     BAR; WAIT_L(0); MMA(0, 1, At, B1); BAR;
;     LDA(At, 1, 1); STAGE(SA(1, 0), A, 0, brow, t + 3);
;     BAR; WAIT_L(0); MMA(1, 0, At, B0); BAR; SCHED;
;     STAGE(SB(1, 1), Bt, 0, bcol + HALF, t + 3);
;     WAIT_V(6); BAR; MMA(1, 1, At, B1); BAR;
	s_setprio 1
	v_mfma_f32_16x16x32_bf16 v[28:31], v[150:153], v[212:215], v[28:31]
	v_mfma_f32_16x16x32_bf16 v[24:27], v[150:153], v[220:223], v[24:27]
	v_mfma_f32_16x16x32_bf16 v[20:23], v[188:191], v[212:215], v[20:23]
	v_mfma_f32_16x16x32_bf16 v[16:19], v[188:191], v[220:223], v[16:19]
	v_mfma_f32_16x16x32_bf16 v[12:15], v[196:199], v[212:215], v[12:15]
	v_mfma_f32_16x16x32_bf16 v[8:11], v[196:199], v[220:223], v[8:11]
	v_mfma_f32_16x16x32_bf16 v[4:7], v[204:207], v[212:215], v[4:7]
	v_mfma_f32_16x16x32_bf16 v[0:3], v[204:207], v[220:223], v[0:3]
	v_mfma_f32_16x16x32_bf16 v[28:31], v[154:157], v[216:219], v[28:31]
	v_mfma_f32_16x16x32_bf16 v[24:27], v[154:157], v[224:227], v[24:27]
	v_mfma_f32_16x16x32_bf16 v[20:23], v[192:195], v[216:219], v[20:23]
	v_mfma_f32_16x16x32_bf16 v[16:19], v[192:195], v[224:227], v[16:19]
	v_mfma_f32_16x16x32_bf16 v[12:15], v[200:203], v[216:219], v[12:15]
	v_mfma_f32_16x16x32_bf16 v[8:11], v[200:203], v[224:227], v[8:11]
	v_mfma_f32_16x16x32_bf16 v[4:7], v[208:211], v[216:219], v[4:7]
	v_mfma_f32_16x16x32_bf16 v[0:3], v[208:211], v[224:227], v[0:3]
	s_setprio 0
	s_barrier
	ds_read_b128 v[134:137], v131
	ds_read_b128 v[138:141], v131 offset:1024
	ds_read_b128 v[142:145], v131 offset:2048
	ds_read_b128 v[146:149], v131 offset:3072
	s_add_u32 s68, vcc_lo, 0x100
	s_addc_u32 s69, vcc_hi, 0
	s_mov_b32 m0, s40
	ds_read_b128 v[150:153], v171 offset:32768
	ds_read_b128 v[154:157], v171 offset:33792
	ds_read_b128 v[188:191], v170 offset:32768
	ds_read_b128 v[192:195], v170 offset:33792
	ds_read_b128 v[196:199], v169 offset:32768
	ds_read_b128 v[200:203], v169 offset:33792
	ds_read_b128 v[204:207], v167 offset:32768
	ds_read_b128 v[208:211], v167 offset:33792
	s_nop 0
	global_load_lds_dwordx4 v128, s[68:69]
	s_mov_b32 m0, s41
	s_nop 0
	global_load_lds_dwordx4 v129, s[68:69]
	s_waitcnt lgkmcnt(8)
	s_barrier
	s_waitcnt lgkmcnt(0)
	s_setprio 1
	s_waitcnt lgkmcnt(0)
	v_mfma_f32_16x16x32_bf16 v[124:127], v[150:153], v[134:137], v[124:127]
	v_mfma_f32_16x16x32_bf16 v[120:123], v[150:153], v[142:145], v[120:123]
	v_mfma_f32_16x16x32_bf16 v[116:119], v[188:191], v[134:137], v[116:119]
	v_mfma_f32_16x16x32_bf16 v[112:115], v[188:191], v[142:145], v[112:115]
	v_mfma_f32_16x16x32_bf16 v[108:111], v[196:199], v[134:137], v[108:111]
	v_mfma_f32_16x16x32_bf16 v[104:107], v[196:199], v[142:145], v[104:107]
	v_mfma_f32_16x16x32_bf16 v[100:103], v[204:207], v[134:137], v[100:103]
	v_mfma_f32_16x16x32_bf16 v[96:99], v[204:207], v[142:145], v[96:99]
	v_mfma_f32_16x16x32_bf16 v[124:127], v[154:157], v[138:141], v[124:127]
	v_mfma_f32_16x16x32_bf16 v[120:123], v[154:157], v[146:149], v[120:123]
	v_mfma_f32_16x16x32_bf16 v[116:119], v[192:195], v[138:141], v[116:119]
	v_mfma_f32_16x16x32_bf16 v[112:115], v[192:195], v[146:149], v[112:115]
	v_mfma_f32_16x16x32_bf16 v[108:111], v[200:203], v[138:141], v[108:111]
	v_mfma_f32_16x16x32_bf16 v[104:107], v[200:203], v[146:149], v[104:107]
	v_mfma_f32_16x16x32_bf16 v[100:103], v[208:211], v[138:141], v[100:103]
	v_mfma_f32_16x16x32_bf16 v[96:99], v[208:211], v[146:149], v[96:99]
	s_setprio 0
	s_barrier
	s_add_u32 s68, s51, 0x180
	s_addc_u32 s69, s72, 0
	s_add_i32 m0, s22, 0x18000
	ds_read_b128 v[212:215], v130
	ds_read_b128 v[216:219], v130 offset:1024
	ds_read_b128 v[220:223], v130 offset:2048
	ds_read_b128 v[224:227], v130 offset:3072
	s_nop 0
	global_load_lds_dwordx4 v128, s[68:69]
	s_add_i32 m0, s22, 0x1a000
	s_nop 0
	global_load_lds_dwordx4 v129, s[68:69]
	s_barrier
	s_waitcnt lgkmcnt(0)
	s_setprio 1
	s_waitcnt lgkmcnt(0)
	v_mfma_f32_16x16x32_bf16 v[92:95], v[150:153], v[212:215], v[92:95]
	v_mfma_f32_16x16x32_bf16 v[88:91], v[150:153], v[220:223], v[88:91]
	v_mfma_f32_16x16x32_bf16 v[84:87], v[188:191], v[212:215], v[84:87]
	v_mfma_f32_16x16x32_bf16 v[80:83], v[188:191], v[220:223], v[80:83]
	v_mfma_f32_16x16x32_bf16 v[76:79], v[196:199], v[212:215], v[76:79]
	v_mfma_f32_16x16x32_bf16 v[72:75], v[196:199], v[220:223], v[72:75]
	v_mfma_f32_16x16x32_bf16 v[68:71], v[204:207], v[212:215], v[68:71]
	v_mfma_f32_16x16x32_bf16 v[64:67], v[204:207], v[220:223], v[64:67]
	v_mfma_f32_16x16x32_bf16 v[92:95], v[154:157], v[216:219], v[92:95]
	v_mfma_f32_16x16x32_bf16 v[88:91], v[154:157], v[224:227], v[88:91]
	v_mfma_f32_16x16x32_bf16 v[84:87], v[192:195], v[216:219], v[84:87]
	v_mfma_f32_16x16x32_bf16 v[80:83], v[192:195], v[224:227], v[80:83]
	v_mfma_f32_16x16x32_bf16 v[76:79], v[200:203], v[216:219], v[76:79]
	v_mfma_f32_16x16x32_bf16 v[72:75], v[200:203], v[224:227], v[72:75]
	v_mfma_f32_16x16x32_bf16 v[68:71], v[208:211], v[216:219], v[68:71]
	v_mfma_f32_16x16x32_bf16 v[64:67], v[208:211], v[224:227], v[64:67]
	s_setprio 0
	s_add_u32 s68, s73, 0x180
	s_addc_u32 s69, s78, 0
	s_mov_b32 m0, s18
	s_barrier
	ds_read_b128 v[150:153], v171 offset:49152
	ds_read_b128 v[154:157], v171 offset:50176
	ds_read_b128 v[188:191], v170 offset:49152
	ds_read_b128 v[192:195], v170 offset:50176
	ds_read_b128 v[196:199], v169 offset:49152
	ds_read_b128 v[200:203], v169 offset:50176
	ds_read_b128 v[204:207], v167 offset:49152
	ds_read_b128 v[208:211], v167 offset:50176
	s_nop 0
	global_load_lds_dwordx4 v128, s[68:69]
	s_mov_b32 m0, s19
	s_nop 0
	global_load_lds_dwordx4 v129, s[68:69]
	s_barrier
; #define LDA(dst, b, h) for (int m = 0; m < 4; ++m) for (int k = 0; k < 2; ++k) \
;     dst[m][k] = *reinterpret_cast<const bf16x8*>((char*)SA(b, h) + lds_byte(wr * 64 + m * 16 + fr, k * 32 + fq * 8))
; #define LDB(dst, b, h) for (int n = 0; n < 2; ++n) for (int k = 0; k < 2; ++k) \
;     dst[n][k] = *reinterpret_cast<const bf16x8*>((char*)SB(b, h) + lds_byte(wc * 32 + n * 16 + fr, k * 32 + fq * 8))
; #define MMA(ai, bj, At, Bt_) do { __builtin_amdgcn_s_setprio(1); \
;     for (int m = 0; m < 4; ++m) for (int n = 0; n < 2; ++n) for (int k = 0; k < 2; ++k) \
;       acc[ai][bj][m][n] = __builtin_amdgcn_mfma_f32_16x16x32_bf16(At[m][k], Bt_[n][k], acc[ai][bj][m][n], 0, 0, 0); \
;     __builtin_amdgcn_s_setprio(0); } while (0)
; #define WAIT_V(n) asm volatile("s_waitcnt vmcnt(" #n ")" ::: "memory")
; #define WAIT_L(n) asm volatile("s_waitcnt lgkmcnt(" #n ")" ::: "memory")
; #define BAR __builtin_amdgcn_s_barrier()
; #define SCHED __builtin_amdgcn_sched_barrier(0)
; __device__ __forceinline__ void gemm_tile(const bf16_t* __restrict__ A, const bf16_t* __restrict__ Bt, int K, int brow, int bcol,
;                                           int mode, const Params& p, char* wsb, const float* xg, float* outg, int S, char* shmc) {
;     ...
;   for (int t = 0; t < nt - 2; t += 2) {
;     LDB(B0, 0, 0); SCHED; LDA(At, 0, 0); STAGE(SA(1, 1), A, 0, brow + HALF, t + 1);
;     WAIT_L(8); BAR; WAIT_L(0); MMA(0, 0, At, B0); BAR; SCHED;
;     LDB(B1, 0, 1); STAGE(SB(0, 0), Bt, 0, bcol, t + 2);
;     BAR; WAIT_L(0); MMA(0, 1, At, B1); BAR;
;     LDA(At, 0, 1); STAGE(SA(0, 0), A, 0, brow, t + 2);
;     BAR; WAIT_L(0); MMA(1, 0, At, B0); BAR; SCHED;
;     STAGE(SB(0, 1), Bt, 0, bcol + HALF, t + 2);
;     WAIT_V(6); BAR; MMA(1, 1, At, B1); BAR;
;     LDB(B0, 1, 0); SCHED; LDA(At, 1, 0); STAGE(SA(0, 1), A, 0, brow + HALF, t + 2);
;     WAIT_L(8); BAR; WAIT_L(0); MMA(0, 0, At, B0); BAR; SCHED;
;     LDB(B1, 1, 1); STAGE(SB(1, 0), Bt, 0, bcol, t + 3);
;     BAR; WAIT_L(0); MMA(0, 1, At, B1); BAR;
;     LDA(At, 1, 1); STAGE(SA(1, 0), A, 0, brow, t + 3);
;     BAR; WAIT_L(0); MMA(1, 0, At, B0); BAR; SCHED;
;     STAGE(SB(1, 1), Bt, 0, bcol + HALF, t + 3);
;     WAIT_V(6); BAR; MMA(1, 1, At, B1); BAR;
;   }
	s_waitcnt lgkmcnt(0)
	s_setprio 1
	s_waitcnt lgkmcnt(0)
	v_mfma_f32_16x16x32_bf16 v[60:63], v[150:153], v[134:137], v[60:63]
	v_mfma_f32_16x16x32_bf16 v[56:59], v[150:153], v[142:145], v[56:59]
	v_mfma_f32_16x16x32_bf16 v[52:55], v[188:191], v[134:137], v[52:55]
	v_mfma_f32_16x16x32_bf16 v[48:51], v[188:191], v[142:145], v[48:51]
	v_mfma_f32_16x16x32_bf16 v[44:47], v[196:199], v[134:137], v[44:47]
	v_mfma_f32_16x16x32_bf16 v[40:43], v[196:199], v[142:145], v[40:43]
	v_mfma_f32_16x16x32_bf16 v[36:39], v[204:207], v[134:137], v[36:39]
	v_mfma_f32_16x16x32_bf16 v[32:35], v[204:207], v[142:145], v[32:35]
	v_mfma_f32_16x16x32_bf16 v[60:63], v[154:157], v[138:141], v[60:63]
	v_mfma_f32_16x16x32_bf16 v[56:59], v[154:157], v[146:149], v[56:59]
	v_mfma_f32_16x16x32_bf16 v[52:55], v[192:195], v[138:141], v[52:55]
	v_mfma_f32_16x16x32_bf16 v[48:51], v[192:195], v[146:149], v[48:51]
	v_mfma_f32_16x16x32_bf16 v[44:47], v[200:203], v[138:141], v[44:47]
	v_mfma_f32_16x16x32_bf16 v[40:43], v[200:203], v[146:149], v[40:43]
	v_mfma_f32_16x16x32_bf16 v[36:39], v[208:211], v[138:141], v[36:39]
	v_mfma_f32_16x16x32_bf16 v[32:35], v[208:211], v[146:149], v[32:35]
	s_setprio 0
	s_barrier
	s_add_u32 s68, s79, 0x180
	s_addc_u32 s69, s80, 0
	s_add_i32 m0, s22, 0x1c000
	s_nop 0
	global_load_lds_dwordx4 v128, s[68:69]
	s_add_i32 m0, s22, 0x1e000
	s_nop 0
	global_load_lds_dwordx4 v129, s[68:69]
	s_waitcnt vmcnt(6)
	s_barrier
	s_setprio 1
	v_mfma_f32_16x16x32_bf16 v[28:31], v[150:153], v[212:215], v[28:31]
	v_mfma_f32_16x16x32_bf16 v[24:27], v[150:153], v[220:223], v[24:27]
	v_mfma_f32_16x16x32_bf16 v[20:23], v[188:191], v[212:215], v[20:23]
	v_mfma_f32_16x16x32_bf16 v[16:19], v[188:191], v[220:223], v[16:19]
	v_mfma_f32_16x16x32_bf16 v[12:15], v[196:199], v[212:215], v[12:15]
	v_mfma_f32_16x16x32_bf16 v[8:11], v[196:199], v[220:223], v[8:11]
	v_mfma_f32_16x16x32_bf16 v[4:7], v[204:207], v[212:215], v[4:7]
	v_mfma_f32_16x16x32_bf16 v[0:3], v[204:207], v[220:223], v[0:3]
	v_mfma_f32_16x16x32_bf16 v[28:31], v[154:157], v[216:219], v[28:31]
	v_mfma_f32_16x16x32_bf16 v[24:27], v[154:157], v[224:227], v[24:27]
	v_mfma_f32_16x16x32_bf16 v[20:23], v[192:195], v[216:219], v[20:23]
	v_mfma_f32_16x16x32_bf16 v[16:19], v[192:195], v[224:227], v[16:19]
	v_mfma_f32_16x16x32_bf16 v[12:15], v[200:203], v[216:219], v[12:15]
	v_mfma_f32_16x16x32_bf16 v[8:11], v[200:203], v[224:227], v[8:11]
	v_mfma_f32_16x16x32_bf16 v[4:7], v[208:211], v[216:219], v[4:7]
	v_mfma_f32_16x16x32_bf16 v[0:3], v[208:211], v[224:227], v[0:3]
	s_setprio 0
	s_add_u32 s14, s14, 0x100
	s_addc_u32 s15, s15, 0
	s_cmp_lt_u32 s44, s70
	s_barrier
	s_cbranch_scc1 .LBB0_169
	s_branch .Lgm_join
.Lgm_y:
	ds_read_b128 v[134:137], v133
	ds_read_b128 v[138:141], v133 offset:1024
	ds_read_b128 v[142:145], v133 offset:2048
	ds_read_b128 v[146:149], v133 offset:3072
	s_add_u32 vcc_lo, s42, s14
	s_addc_u32 vcc_hi, s43, s15
	s_add_u32 s68, vcc_lo, 0x80
	s_addc_u32 s69, vcc_hi, 0
	s_add_i32 s98, s22, 0xc000
	s_mov_b32 m0, s98
	s_add_i32 s99, s22, 0xe000
	ds_read_b128 v[150:153], v171
	ds_read_b128 v[154:157], v171 offset:1024
	ds_read_b128 v[188:191], v170
	ds_read_b128 v[192:195], v170 offset:1024
	ds_read_b128 v[196:199], v169
	ds_read_b128 v[200:203], v169 offset:1024
	ds_read_b128 v[204:207], v167
	ds_read_b128 v[208:211], v167 offset:1024
	s_nop 0
	global_load_lds_dwordx4 v128, s[68:69]
	s_mov_b32 m0, s99
	s_nop 0
	global_load_lds_dwordx4 v129, s[68:69]
	s_waitcnt lgkmcnt(8)
	s_barrier
	s_waitcnt lgkmcnt(0)
	s_setprio 2
	s_waitcnt lgkmcnt(0)
	v_mfma_f32_16x16x32_bf16 v[124:127], v[150:153], v[134:137], v[124:127]
	v_mfma_f32_16x16x32_bf16 v[120:123], v[150:153], v[142:145], v[120:123]
	v_mfma_f32_16x16x32_bf16 v[116:119], v[188:191], v[134:137], v[116:119]
	v_mfma_f32_16x16x32_bf16 v[112:115], v[188:191], v[142:145], v[112:115]
	v_mfma_f32_16x16x32_bf16 v[108:111], v[196:199], v[134:137], v[108:111]
	v_mfma_f32_16x16x32_bf16 v[104:107], v[196:199], v[142:145], v[104:107]
	v_mfma_f32_16x16x32_bf16 v[100:103], v[204:207], v[134:137], v[100:103]
	v_mfma_f32_16x16x32_bf16 v[96:99], v[204:207], v[142:145], v[96:99]
	v_mfma_f32_16x16x32_bf16 v[124:127], v[154:157], v[138:141], v[124:127]
	v_mfma_f32_16x16x32_bf16 v[120:123], v[154:157], v[146:149], v[120:123]
	v_mfma_f32_16x16x32_bf16 v[116:119], v[192:195], v[138:141], v[116:119]
	v_mfma_f32_16x16x32_bf16 v[112:115], v[192:195], v[146:149], v[112:115]
	v_mfma_f32_16x16x32_bf16 v[108:111], v[200:203], v[138:141], v[108:111]
	v_mfma_f32_16x16x32_bf16 v[104:107], v[200:203], v[146:149], v[104:107]
	v_mfma_f32_16x16x32_bf16 v[100:103], v[208:211], v[138:141], v[100:103]
	v_mfma_f32_16x16x32_bf16 v[96:99], v[208:211], v[146:149], v[96:99]
	s_setprio 1
	s_barrier
	s_add_i32 s44, s44, 2
	s_add_u32 s51, s4, s14
	s_addc_u32 s72, s5, s15
	s_add_u32 s68, s51, 0x100
	s_addc_u32 s69, s72, 0
	s_mov_b32 m0, s23
	ds_read_b128 v[212:215], v132
	ds_read_b128 v[216:219], v132 offset:1024
	ds_read_b128 v[220:223], v132 offset:2048
	ds_read_b128 v[224:227], v132 offset:3072
	s_nop 0
	global_load_lds_dwordx4 v128, s[68:69]
	s_mov_b32 m0, s24
	s_nop 0
	global_load_lds_dwordx4 v129, s[68:69]
	s_barrier
; #define LDA(dst, b, h) for (int m = 0; m < 4; ++m) for (int k = 0; k < 2; ++k) \
;     dst[m][k] = *reinterpret_cast<const bf16x8*>((char*)SA(b, h) + lds_byte(wr * 64 + m * 16 + fr, k * 32 + fq * 8))
; #define LDB(dst, b, h) for (int n = 0; n < 2; ++n) for (int k = 0; k < 2; ++k) \
;     dst[n][k] = *reinterpret_cast<const bf16x8*>((char*)SB(b, h) + lds_byte(wc * 32 + n * 16 + fr, k * 32 + fq * 8))
; #define MMA(ai, bj, At, Bt_) do { __builtin_amdgcn_s_setprio(1); \
;     for (int m = 0; m < 4; ++m) for (int n = 0; n < 2; ++n) for (int k = 0; k < 2; ++k) \
;       acc[ai][bj][m][n] = __builtin_amdgcn_mfma_f32_16x16x32_bf16(At[m][k], Bt_[n][k], acc[ai][bj][m][n], 0, 0, 0); \
;     __builtin_amdgcn_s_setprio(0); } while (0)
; #define WAIT_V(n) asm volatile("s_waitcnt vmcnt(" #n ")" ::: "memory")
; #define WAIT_L(n) asm volatile("s_waitcnt lgkmcnt(" #n ")" ::: "memory")
; #define BAR __builtin_amdgcn_s_barrier()
; #define SCHED __builtin_amdgcn_sched_barrier(0)
; __device__ __forceinline__ void gemm_tile(const bf16_t* __restrict__ A, const bf16_t* __restrict__ Bt, int K, int brow, int bcol,
;                                           int mode, const Params& p, char* wsb, const float* xg, float* outg, int S, char* shmc) {
;     ...
;   for (int t = 0; t < nt - 2; t += 2) {
;     LDB(B0, 0, 0); SCHED; LDA(At, 0, 0); STAGE(SA(1, 1), A, 0, brow + HALF, t + 1);
;     WAIT_L(8); BAR; WAIT_L(0); MMA(0, 0, At, B0); BAR; SCHED;
;     LDB(B1, 0, 1); STAGE(SB(0, 0), Bt, 0, bcol, t + 2);
;     BAR; WAIT_L(0); MMA(0, 1, At, B1); BAR;
;     LDA(At, 0, 1); STAGE(SA(0, 0), A, 0, brow, t + 2);
;     BAR; WAIT_L(0); MMA(1, 0, At, B0); BAR; SCHED;
;     STAGE(SB(0, 1), Bt, 0, bcol + HALF, t + 2);
;     WAIT_V(6); BAR; MMA(1, 1, At, B1); BAR;
;     LDB(B0, 1, 0); SCHED; LDA(At, 1, 0); STAGE(SA(0, 1), A, 0, brow + HALF, t + 2);
;     WAIT_L(8); BAR; WAIT_L(0); MMA(0, 0, At, B0); BAR; SCHED;
;     LDB(B1, 1, 1); STAGE(SB(1, 0), Bt, 0, bcol, t + 3);
;     BAR; WAIT_L(0); MMA(0, 1, At, B1); BAR;
;     LDA(At, 1, 1); STAGE(SA(1, 0), A, 0, brow, t + 3);
;     BAR; WAIT_L(0); MMA(1, 0, At, B0); BAR; SCHED;
;     STAGE(SB(1, 1), Bt, 0, bcol + HALF, t + 3);
;     WAIT_V(6); BAR; MMA(1, 1, At, B1); BAR;
	s_waitcnt lgkmcnt(0)
	s_setprio 2
	s_waitcnt lgkmcnt(0)
	v_mfma_f32_16x16x32_bf16 v[92:95], v[150:153], v[212:215], v[92:95]
	v_mfma_f32_16x16x32_bf16 v[88:91], v[150:153], v[220:223], v[88:91]
	v_mfma_f32_16x16x32_bf16 v[84:87], v[188:191], v[212:215], v[84:87]
	v_mfma_f32_16x16x32_bf16 v[80:83], v[188:191], v[220:223], v[80:83]
	v_mfma_f32_16x16x32_bf16 v[76:79], v[196:199], v[212:215], v[76:79]
	v_mfma_f32_16x16x32_bf16 v[72:75], v[196:199], v[220:223], v[72:75]
	v_mfma_f32_16x16x32_bf16 v[68:71], v[204:207], v[212:215], v[68:71]
	v_mfma_f32_16x16x32_bf16 v[64:67], v[204:207], v[220:223], v[64:67]
	v_mfma_f32_16x16x32_bf16 v[92:95], v[154:157], v[216:219], v[92:95]
	v_mfma_f32_16x16x32_bf16 v[88:91], v[154:157], v[224:227], v[88:91]
	v_mfma_f32_16x16x32_bf16 v[84:87], v[192:195], v[216:219], v[84:87]
	v_mfma_f32_16x16x32_bf16 v[80:83], v[192:195], v[224:227], v[80:83]
	v_mfma_f32_16x16x32_bf16 v[76:79], v[200:203], v[216:219], v[76:79]
	v_mfma_f32_16x16x32_bf16 v[72:75], v[200:203], v[224:227], v[72:75]
	v_mfma_f32_16x16x32_bf16 v[68:71], v[208:211], v[216:219], v[68:71]
	v_mfma_f32_16x16x32_bf16 v[64:67], v[208:211], v[224:227], v[64:67]
	s_setprio 1
	s_add_u32 s73, s20, s14
	s_addc_u32 s78, s21, s15
	s_add_u32 s68, s73, 0x100
	s_addc_u32 s69, s78, 0
	s_mov_b32 m0, s22
	s_barrier
	ds_read_b128 v[150:153], v171 offset:16384
	ds_read_b128 v[154:157], v171 offset:17408
	ds_read_b128 v[188:191], v170 offset:16384
	ds_read_b128 v[192:195], v170 offset:17408
	ds_read_b128 v[196:199], v169 offset:16384
	ds_read_b128 v[200:203], v169 offset:17408
	ds_read_b128 v[204:207], v167 offset:16384
	ds_read_b128 v[208:211], v167 offset:17408
	s_nop 0
	global_load_lds_dwordx4 v128, s[68:69]
	s_mov_b32 m0, s25
	s_nop 0
	global_load_lds_dwordx4 v129, s[68:69]
	s_barrier
	s_waitcnt lgkmcnt(0)
	s_setprio 2
	s_waitcnt lgkmcnt(0)
	v_mfma_f32_16x16x32_bf16 v[60:63], v[150:153], v[134:137], v[60:63]
	v_mfma_f32_16x16x32_bf16 v[56:59], v[150:153], v[142:145], v[56:59]
	v_mfma_f32_16x16x32_bf16 v[52:55], v[188:191], v[134:137], v[52:55]
	v_mfma_f32_16x16x32_bf16 v[48:51], v[188:191], v[142:145], v[48:51]
	v_mfma_f32_16x16x32_bf16 v[44:47], v[196:199], v[134:137], v[44:47]
	v_mfma_f32_16x16x32_bf16 v[40:43], v[196:199], v[142:145], v[40:43]
	v_mfma_f32_16x16x32_bf16 v[36:39], v[204:207], v[134:137], v[36:39]
	v_mfma_f32_16x16x32_bf16 v[32:35], v[204:207], v[142:145], v[32:35]
	v_mfma_f32_16x16x32_bf16 v[60:63], v[154:157], v[138:141], v[60:63]
	v_mfma_f32_16x16x32_bf16 v[56:59], v[154:157], v[146:149], v[56:59]
	v_mfma_f32_16x16x32_bf16 v[52:55], v[192:195], v[138:141], v[52:55]
	v_mfma_f32_16x16x32_bf16 v[48:51], v[192:195], v[146:149], v[48:51]
	v_mfma_f32_16x16x32_bf16 v[44:47], v[200:203], v[138:141], v[44:47]
	v_mfma_f32_16x16x32_bf16 v[40:43], v[200:203], v[146:149], v[40:43]
	v_mfma_f32_16x16x32_bf16 v[36:39], v[208:211], v[138:141], v[36:39]
	v_mfma_f32_16x16x32_bf16 v[32:35], v[208:211], v[146:149], v[32:35]
	s_setprio 1
	s_barrier
	s_add_u32 s79, s16, s14
	s_addc_u32 s80, s17, s15
	s_add_u32 s68, s79, 0x100
	s_addc_u32 s69, s80, 0
	s_mov_b32 m0, s26
	s_nop 0
	global_load_lds_dwordx4 v128, s[68:69]
	s_mov_b32 m0, s27
	s_nop 0
	global_load_lds_dwordx4 v129, s[68:69]
	s_waitcnt vmcnt(6)
	s_barrier
	s_setprio 2
	v_mfma_f32_16x16x32_bf16 v[28:31], v[150:153], v[212:215], v[28:31]
	v_mfma_f32_16x16x32_bf16 v[24:27], v[150:153], v[220:223], v[24:27]
	v_mfma_f32_16x16x32_bf16 v[20:23], v[188:191], v[212:215], v[20:23]
	v_mfma_f32_16x16x32_bf16 v[16:19], v[188:191], v[220:223], v[16:19]
	v_mfma_f32_16x16x32_bf16 v[12:15], v[196:199], v[212:215], v[12:15]
	v_mfma_f32_16x16x32_bf16 v[8:11], v[196:199], v[220:223], v[8:11]
	v_mfma_f32_16x16x32_bf16 v[4:7], v[204:207], v[212:215], v[4:7]
	v_mfma_f32_16x16x32_bf16 v[0:3], v[204:207], v[220:223], v[0:3]
	v_mfma_f32_16x16x32_bf16 v[28:31], v[154:157], v[216:219], v[28:31]
	v_mfma_f32_16x16x32_bf16 v[24:27], v[154:157], v[224:227], v[24:27]
	v_mfma_f32_16x16x32_bf16 v[20:23], v[192:195], v[216:219], v[20:23]
	v_mfma_f32_16x16x32_bf16 v[16:19], v[192:195], v[224:227], v[16:19]
	v_mfma_f32_16x16x32_bf16 v[12:15], v[200:203], v[216:219], v[12:15]
	v_mfma_f32_16x16x32_bf16 v[8:11], v[200:203], v[224:227], v[8:11]
	v_mfma_f32_16x16x32_bf16 v[4:7], v[208:211], v[216:219], v[4:7]
	v_mfma_f32_16x16x32_bf16 v[0:3], v[208:211], v[224:227], v[0:3]
	s_setprio 1
	s_barrier
	ds_read_b128 v[134:137], v131
	ds_read_b128 v[138:141], v131 offset:1024
	ds_read_b128 v[142:145], v131 offset:2048
	ds_read_b128 v[146:149], v131 offset:3072
	s_add_u32 s68, vcc_lo, 0x100
	s_addc_u32 s69, vcc_hi, 0
	s_mov_b32 m0, s40
	ds_read_b128 v[150:153], v171 offset:32768
	ds_read_b128 v[154:157], v171 offset:33792
	ds_read_b128 v[188:191], v170 offset:32768
	ds_read_b128 v[192:195], v170 offset:33792
	ds_read_b128 v[196:199], v169 offset:32768
	ds_read_b128 v[200:203], v169 offset:33792
	ds_read_b128 v[204:207], v167 offset:32768
	ds_read_b128 v[208:211], v167 offset:33792
	s_nop 0
	global_load_lds_dwordx4 v128, s[68:69]
	s_mov_b32 m0, s41
	s_nop 0
	global_load_lds_dwordx4 v129, s[68:69]
	s_waitcnt lgkmcnt(8)
	s_barrier
; #define LDA(dst, b, h) for (int m = 0; m < 4; ++m) for (int k = 0; k < 2; ++k) \
;     dst[m][k] = *reinterpret_cast<const bf16x8*>((char*)SA(b, h) + lds_byte(wr * 64 + m * 16 + fr, k * 32 + fq * 8))
; #define LDB(dst, b, h) for (int n = 0; n < 2; ++n) for (int k = 0; k < 2; ++k) \
;     dst[n][k] = *reinterpret_cast<const bf16x8*>((char*)SB(b, h) + lds_byte(wc * 32 + n * 16 + fr, k * 32 + fq * 8))
; #define MMA(ai, bj, At, Bt_) do { __builtin_amdgcn_s_setprio(1); \
;     for (int m = 0; m < 4; ++m) for (int n = 0; n < 2; ++n) for (int k = 0; k < 2; ++k) \
;       acc[ai][bj][m][n] = __builtin_amdgcn_mfma_f32_16x16x32_bf16(At[m][k], Bt_[n][k], acc[ai][bj][m][n], 0, 0, 0); \
;     __builtin_amdgcn_s_setprio(0); } while (0)
; #define WAIT_V(n) asm volatile("s_waitcnt vmcnt(" #n ")" ::: "memory")
; #define WAIT_L(n) asm volatile("s_waitcnt lgkmcnt(" #n ")" ::: "memory")
; #define BAR __builtin_amdgcn_s_barrier()
; #define SCHED __builtin_amdgcn_sched_barrier(0)
; __device__ __forceinline__ void gemm_tile(const bf16_t* __restrict__ A, const bf16_t* __restrict__ Bt, int K, int brow, int bcol,
;                                           int mode, const Params& p, char* wsb, const float* xg, float* outg, int S, char* shmc) {
;     ...
;     LDB(B0, 1, 0); SCHED; LDA(At, 1, 0); STAGE(SA(0, 1), A, 0, brow + HALF, t + 2);
;     WAIT_L(8); BAR; WAIT_L(0); MMA(0, 0, At, B0); BAR; SCHED;
;     LDB(B1, 1, 1); STAGE(SB(1, 0), Bt, 0, bcol, t + 3);
;     BAR; WAIT_L(0); MMA(0, 1, At, B1); BAR;
;     LDA(At, 1, 1); STAGE(SA(1, 0), A, 0, brow, t + 3);
;     BAR; WAIT_L(0); MMA(1, 0, At, B0); BAR; SCHED;
;     STAGE(SB(1, 1), Bt, 0, bcol + HALF, t + 3);
;     WAIT_V(6); BAR; MMA(1, 1, At, B1); BAR;
;   }
	s_waitcnt lgkmcnt(0)
	s_setprio 2
	s_waitcnt lgkmcnt(0)
	v_mfma_f32_16x16x32_bf16 v[124:127], v[150:153], v[134:137], v[124:127]
	v_mfma_f32_16x16x32_bf16 v[120:123], v[150:153], v[142:145], v[120:123]
	v_mfma_f32_16x16x32_bf16 v[116:119], v[188:191], v[134:137], v[116:119]
	v_mfma_f32_16x16x32_bf16 v[112:115], v[188:191], v[142:145], v[112:115]
	v_mfma_f32_16x16x32_bf16 v[108:111], v[196:199], v[134:137], v[108:111]
	v_mfma_f32_16x16x32_bf16 v[104:107], v[196:199], v[142:145], v[104:107]
	v_mfma_f32_16x16x32_bf16 v[100:103], v[204:207], v[134:137], v[100:103]
	v_mfma_f32_16x16x32_bf16 v[96:99], v[204:207], v[142:145], v[96:99]
	v_mfma_f32_16x16x32_bf16 v[124:127], v[154:157], v[138:141], v[124:127]
	v_mfma_f32_16x16x32_bf16 v[120:123], v[154:157], v[146:149], v[120:123]
	v_mfma_f32_16x16x32_bf16 v[116:119], v[192:195], v[138:141], v[116:119]
	v_mfma_f32_16x16x32_bf16 v[112:115], v[192:195], v[146:149], v[112:115]
	v_mfma_f32_16x16x32_bf16 v[108:111], v[200:203], v[138:141], v[108:111]
	v_mfma_f32_16x16x32_bf16 v[104:107], v[200:203], v[146:149], v[104:107]
	v_mfma_f32_16x16x32_bf16 v[100:103], v[208:211], v[138:141], v[100:103]
	v_mfma_f32_16x16x32_bf16 v[96:99], v[208:211], v[146:149], v[96:99]
	s_setprio 1
	s_barrier
	s_add_u32 s68, s51, 0x180
	s_addc_u32 s69, s72, 0
	s_add_i32 m0, s22, 0x18000
	ds_read_b128 v[212:215], v130
	ds_read_b128 v[216:219], v130 offset:1024
	ds_read_b128 v[220:223], v130 offset:2048
	ds_read_b128 v[224:227], v130 offset:3072
	s_nop 0
	global_load_lds_dwordx4 v128, s[68:69]
	s_add_i32 m0, s22, 0x1a000
	s_nop 0
	global_load_lds_dwordx4 v129, s[68:69]
	s_barrier
	s_waitcnt lgkmcnt(0)
	s_setprio 2
	s_waitcnt lgkmcnt(0)
	v_mfma_f32_16x16x32_bf16 v[92:95], v[150:153], v[212:215], v[92:95]
	v_mfma_f32_16x16x32_bf16 v[88:91], v[150:153], v[220:223], v[88:91]
	v_mfma_f32_16x16x32_bf16 v[84:87], v[188:191], v[212:215], v[84:87]
	v_mfma_f32_16x16x32_bf16 v[80:83], v[188:191], v[220:223], v[80:83]
	v_mfma_f32_16x16x32_bf16 v[76:79], v[196:199], v[212:215], v[76:79]
	v_mfma_f32_16x16x32_bf16 v[72:75], v[196:199], v[220:223], v[72:75]
	v_mfma_f32_16x16x32_bf16 v[68:71], v[204:207], v[212:215], v[68:71]
	v_mfma_f32_16x16x32_bf16 v[64:67], v[204:207], v[220:223], v[64:67]
	v_mfma_f32_16x16x32_bf16 v[92:95], v[154:157], v[216:219], v[92:95]
	v_mfma_f32_16x16x32_bf16 v[88:91], v[154:157], v[224:227], v[88:91]
	v_mfma_f32_16x16x32_bf16 v[84:87], v[192:195], v[216:219], v[84:87]
	v_mfma_f32_16x16x32_bf16 v[80:83], v[192:195], v[224:227], v[80:83]
	v_mfma_f32_16x16x32_bf16 v[76:79], v[200:203], v[216:219], v[76:79]
	v_mfma_f32_16x16x32_bf16 v[72:75], v[200:203], v[224:227], v[72:75]
	v_mfma_f32_16x16x32_bf16 v[68:71], v[208:211], v[216:219], v[68:71]
	v_mfma_f32_16x16x32_bf16 v[64:67], v[208:211], v[224:227], v[64:67]
	s_setprio 1
	s_add_u32 s68, s73, 0x180
	s_addc_u32 s69, s78, 0
	s_mov_b32 m0, s18
	s_barrier
	ds_read_b128 v[150:153], v171 offset:49152
	ds_read_b128 v[154:157], v171 offset:50176
	ds_read_b128 v[188:191], v170 offset:49152
	ds_read_b128 v[192:195], v170 offset:50176
	ds_read_b128 v[196:199], v169 offset:49152
	ds_read_b128 v[200:203], v169 offset:50176
	ds_read_b128 v[204:207], v167 offset:49152
	ds_read_b128 v[208:211], v167 offset:50176
	s_nop 0
	global_load_lds_dwordx4 v128, s[68:69]
	s_mov_b32 m0, s19
	s_nop 0
	global_load_lds_dwordx4 v129, s[68:69]
	s_barrier
	s_waitcnt lgkmcnt(0)
	s_setprio 2
	s_waitcnt lgkmcnt(0)
	v_mfma_f32_16x16x32_bf16 v[60:63], v[150:153], v[134:137], v[60:63]
	v_mfma_f32_16x16x32_bf16 v[56:59], v[150:153], v[142:145], v[56:59]
	v_mfma_f32_16x16x32_bf16 v[52:55], v[188:191], v[134:137], v[52:55]
	v_mfma_f32_16x16x32_bf16 v[48:51], v[188:191], v[142:145], v[48:51]
	v_mfma_f32_16x16x32_bf16 v[44:47], v[196:199], v[134:137], v[44:47]
	v_mfma_f32_16x16x32_bf16 v[40:43], v[196:199], v[142:145], v[40:43]
	v_mfma_f32_16x16x32_bf16 v[36:39], v[204:207], v[134:137], v[36:39]
	v_mfma_f32_16x16x32_bf16 v[32:35], v[204:207], v[142:145], v[32:35]
	v_mfma_f32_16x16x32_bf16 v[60:63], v[154:157], v[138:141], v[60:63]
	v_mfma_f32_16x16x32_bf16 v[56:59], v[154:157], v[146:149], v[56:59]
	v_mfma_f32_16x16x32_bf16 v[52:55], v[192:195], v[138:141], v[52:55]
	v_mfma_f32_16x16x32_bf16 v[48:51], v[192:195], v[146:149], v[48:51]
	v_mfma_f32_16x16x32_bf16 v[44:47], v[200:203], v[138:141], v[44:47]
	v_mfma_f32_16x16x32_bf16 v[40:43], v[200:203], v[146:149], v[40:43]
	v_mfma_f32_16x16x32_bf16 v[36:39], v[208:211], v[138:141], v[36:39]
	v_mfma_f32_16x16x32_bf16 v[32:35], v[208:211], v[146:149], v[32:35]
	s_setprio 1
	s_barrier
	s_add_u32 s68, s79, 0x180
	s_addc_u32 s69, s80, 0
	s_add_i32 m0, s22, 0x1c000
	s_nop 0
	global_load_lds_dwordx4 v128, s[68:69]
	s_add_i32 m0, s22, 0x1e000
	s_nop 0
	global_load_lds_dwordx4 v129, s[68:69]
	s_waitcnt vmcnt(6)
	s_barrier
	s_setprio 2
	v_mfma_f32_16x16x32_bf16 v[28:31], v[150:153], v[212:215], v[28:31]
	v_mfma_f32_16x16x32_bf16 v[24:27], v[150:153], v[220:223], v[24:27]
	v_mfma_f32_16x16x32_bf16 v[20:23], v[188:191], v[212:215], v[20:23]
	v_mfma_f32_16x16x32_bf16 v[16:19], v[188:191], v[220:223], v[16:19]
	v_mfma_f32_16x16x32_bf16 v[12:15], v[196:199], v[212:215], v[12:15]
	v_mfma_f32_16x16x32_bf16 v[8:11], v[196:199], v[220:223], v[8:11]
	v_mfma_f32_16x16x32_bf16 v[4:7], v[204:207], v[212:215], v[4:7]
	v_mfma_f32_16x16x32_bf16 v[0:3], v[204:207], v[220:223], v[0:3]
	v_mfma_f32_16x16x32_bf16 v[28:31], v[154:157], v[216:219], v[28:31]
	v_mfma_f32_16x16x32_bf16 v[24:27], v[154:157], v[224:227], v[24:27]
	v_mfma_f32_16x16x32_bf16 v[20:23], v[192:195], v[216:219], v[20:23]
	v_mfma_f32_16x16x32_bf16 v[16:19], v[192:195], v[224:227], v[16:19]
	v_mfma_f32_16x16x32_bf16 v[12:15], v[200:203], v[216:219], v[12:15]
	v_mfma_f32_16x16x32_bf16 v[8:11], v[200:203], v[224:227], v[8:11]
	v_mfma_f32_16x16x32_bf16 v[4:7], v[208:211], v[216:219], v[4:7]
	v_mfma_f32_16x16x32_bf16 v[0:3], v[208:211], v[224:227], v[0:3]
	s_setprio 1
	s_add_u32 s14, s14, 0x100
	s_addc_u32 s15, s15, 0
	s_cmp_lt_u32 s44, s70
	s_barrier
	s_cbranch_scc1 .Lgm_y
	s_setprio 0
; #define LDA(dst, b, h) for (int m = 0; m < 4; ++m) for (int k = 0; k < 2; ++k) \
;     dst[m][k] = *reinterpret_cast<const bf16x8*>((char*)SA(b, h) + lds_byte(wr * 64 + m * 16 + fr, k * 32 + fq * 8))
; #define LDB(dst, b, h) for (int n = 0; n < 2; ++n) for (int k = 0; k < 2; ++k) \
;     dst[n][k] = *reinterpret_cast<const bf16x8*>((char*)SB(b, h) + lds_byte(wc * 32 + n * 16 + fr, k * 32 + fq * 8))
; #define MMA(ai, bj, At, Bt_) do { __builtin_amdgcn_s_setprio(1); \
;     for (int m = 0; m < 4; ++m) for (int n = 0; n < 2; ++n) for (int k = 0; k < 2; ++k) \
;       acc[ai][bj][m][n] = __builtin_amdgcn_mfma_f32_16x16x32_bf16(At[m][k], Bt_[n][k], acc[ai][bj][m][n], 0, 0, 0); \
;     __builtin_amdgcn_s_setprio(0); } while (0)
; #define WAIT_V(n) asm volatile("s_waitcnt vmcnt(" #n ")" ::: "memory")
; #define WAIT_L(n) asm volatile("s_waitcnt lgkmcnt(" #n ")" ::: "memory")
; #define BAR __builtin_amdgcn_s_barrier()
; __device__ __forceinline__ void gemm_tile(const bf16_t* __restrict__ A, const bf16_t* __restrict__ Bt, int K, int brow, int bcol,
;                                           int mode, const Params& p, char* wsb, const float* xg, float* outg, int S, char* shmc) {
;     ...
;   { LDB(B0, 0, 0); LDA(At, 0, 0); STAGE(SA(1, 1), A, 0, brow + HALF, nt - 1);
;     BAR; WAIT_L(0); MMA(0, 0, At, B0); BAR;
;     LDB(B1, 0, 1); BAR; WAIT_L(0); MMA(0, 1, At, B1); BAR;
;     LDA(At, 0, 1); WAIT_V(4); BAR; WAIT_L(0); MMA(1, 0, At, B0); MMA(1, 1, At, B1); BAR; }
.Lgm_join:
	s_add_u32 s4, s12, s64
	s_addc_u32 s5, s13, s65
	s_mov_b32 m0, s98
	ds_read_b128 v[134:137], v133
	ds_read_b128 v[138:141], v133 offset:1024
	ds_read_b128 v[142:145], v133 offset:2048
	ds_read_b128 v[146:149], v133 offset:3072
	ds_read_b128 v[150:153], v171
	ds_read_b128 v[154:157], v171 offset:1024
	ds_read_b128 v[188:191], v170
	ds_read_b128 v[192:195], v170 offset:1024
	ds_read_b128 v[196:199], v169
	ds_read_b128 v[200:203], v169 offset:1024
	ds_read_b128 v[204:207], v167
	ds_read_b128 v[208:211], v167 offset:1024
	s_nop 0
	global_load_lds_dwordx4 v128, s[4:5]
	s_mov_b32 m0, s99
	s_nop 0
	global_load_lds_dwordx4 v129, s[4:5]
	s_barrier
	s_waitcnt lgkmcnt(0)
	s_setprio 1
	s_waitcnt lgkmcnt(0)
	v_mfma_f32_16x16x32_bf16 v[124:127], v[150:153], v[134:137], v[124:127]
	v_mfma_f32_16x16x32_bf16 v[120:123], v[150:153], v[142:145], v[120:123]
	v_mfma_f32_16x16x32_bf16 v[116:119], v[188:191], v[134:137], v[116:119]
	v_mfma_f32_16x16x32_bf16 v[112:115], v[188:191], v[142:145], v[112:115]
	v_mfma_f32_16x16x32_bf16 v[108:111], v[196:199], v[134:137], v[108:111]
	v_mfma_f32_16x16x32_bf16 v[104:107], v[196:199], v[142:145], v[104:107]
	v_mfma_f32_16x16x32_bf16 v[100:103], v[204:207], v[134:137], v[100:103]
	v_mfma_f32_16x16x32_bf16 v[96:99], v[204:207], v[142:145], v[96:99]
	v_mfma_f32_16x16x32_bf16 v[124:127], v[154:157], v[138:141], v[124:127]
	v_mfma_f32_16x16x32_bf16 v[120:123], v[154:157], v[146:149], v[120:123]
	v_mfma_f32_16x16x32_bf16 v[116:119], v[192:195], v[138:141], v[116:119]
	v_mfma_f32_16x16x32_bf16 v[112:115], v[192:195], v[146:149], v[112:115]
	v_mfma_f32_16x16x32_bf16 v[108:111], v[200:203], v[138:141], v[108:111]
	v_mfma_f32_16x16x32_bf16 v[104:107], v[200:203], v[146:149], v[104:107]
	v_mfma_f32_16x16x32_bf16 v[100:103], v[208:211], v[138:141], v[100:103]
	v_mfma_f32_16x16x32_bf16 v[96:99], v[208:211], v[146:149], v[96:99]
	s_setprio 0
	s_barrier
	ds_read_b128 v[212:215], v132
	ds_read_b128 v[216:219], v132 offset:1024
	ds_read_b128 v[220:223], v132 offset:2048
	ds_read_b128 v[224:227], v132 offset:3072
	s_barrier
	s_waitcnt lgkmcnt(0)
	s_setprio 1
	s_waitcnt lgkmcnt(0)
	v_mfma_f32_16x16x32_bf16 v[92:95], v[150:153], v[212:215], v[92:95]
	v_mfma_f32_16x16x32_bf16 v[88:91], v[150:153], v[220:223], v[88:91]
	v_mfma_f32_16x16x32_bf16 v[84:87], v[188:191], v[212:215], v[84:87]
	v_mfma_f32_16x16x32_bf16 v[80:83], v[188:191], v[220:223], v[80:83]
	v_mfma_f32_16x16x32_bf16 v[76:79], v[196:199], v[212:215], v[76:79]
	v_mfma_f32_16x16x32_bf16 v[72:75], v[196:199], v[220:223], v[72:75]
	v_mfma_f32_16x16x32_bf16 v[68:71], v[204:207], v[212:215], v[68:71]
	v_mfma_f32_16x16x32_bf16 v[64:67], v[204:207], v[220:223], v[64:67]
	v_mfma_f32_16x16x32_bf16 v[92:95], v[154:157], v[216:219], v[92:95]
	v_mfma_f32_16x16x32_bf16 v[88:91], v[154:157], v[224:227], v[88:91]
	v_mfma_f32_16x16x32_bf16 v[84:87], v[192:195], v[216:219], v[84:87]
	v_mfma_f32_16x16x32_bf16 v[80:83], v[192:195], v[224:227], v[80:83]
	v_mfma_f32_16x16x32_bf16 v[76:79], v[200:203], v[216:219], v[76:79]
	v_mfma_f32_16x16x32_bf16 v[72:75], v[200:203], v[224:227], v[72:75]
	v_mfma_f32_16x16x32_bf16 v[68:71], v[208:211], v[216:219], v[68:71]
	v_mfma_f32_16x16x32_bf16 v[64:67], v[208:211], v[224:227], v[64:67]
	s_setprio 0
	s_barrier
	ds_read_b128 v[150:153], v171 offset:16384
	ds_read_b128 v[154:157], v171 offset:17408
	ds_read_b128 v[188:191], v170 offset:16384
	ds_read_b128 v[192:195], v170 offset:17408
	ds_read_b128 v[196:199], v169 offset:16384
	ds_read_b128 v[200:203], v169 offset:17408
	ds_read_b128 v[204:207], v167 offset:16384
	ds_read_b128 v[208:211], v167 offset:17408
	s_waitcnt vmcnt(4)
	s_barrier
	s_waitcnt lgkmcnt(0)
	s_setprio 1
	s_waitcnt lgkmcnt(0)
	v_mfma_f32_16x16x32_bf16 v[60:63], v[150:153], v[134:137], v[60:63]
	v_mfma_f32_16x16x32_bf16 v[56:59], v[150:153], v[142:145], v[56:59]
	v_mfma_f32_16x16x32_bf16 v[52:55], v[188:191], v[134:137], v[52:55]
	v_mfma_f32_16x16x32_bf16 v[48:51], v[188:191], v[142:145], v[48:51]
	v_mfma_f32_16x16x32_bf16 v[44:47], v[196:199], v[134:137], v[44:47]
	v_mfma_f32_16x16x32_bf16 v[40:43], v[196:199], v[142:145], v[40:43]
	v_mfma_f32_16x16x32_bf16 v[36:39], v[204:207], v[134:137], v[36:39]
	v_mfma_f32_16x16x32_bf16 v[32:35], v[204:207], v[142:145], v[32:35]
	v_mfma_f32_16x16x32_bf16 v[60:63], v[154:157], v[138:141], v[60:63]
	v_mfma_f32_16x16x32_bf16 v[56:59], v[154:157], v[146:149], v[56:59]
	v_mfma_f32_16x16x32_bf16 v[52:55], v[192:195], v[138:141], v[52:55]
	v_mfma_f32_16x16x32_bf16 v[48:51], v[192:195], v[146:149], v[48:51]
	v_mfma_f32_16x16x32_bf16 v[44:47], v[200:203], v[138:141], v[44:47]
	v_mfma_f32_16x16x32_bf16 v[40:43], v[200:203], v[146:149], v[40:43]
	v_mfma_f32_16x16x32_bf16 v[36:39], v[208:211], v[138:141], v[36:39]
	v_mfma_f32_16x16x32_bf16 v[32:35], v[208:211], v[146:149], v[32:35]
	s_setprio 0
	s_setprio 1
	v_mfma_f32_16x16x32_bf16 v[28:31], v[150:153], v[212:215], v[28:31]
	v_mfma_f32_16x16x32_bf16 v[24:27], v[150:153], v[220:223], v[24:27]
	v_mfma_f32_16x16x32_bf16 v[20:23], v[188:191], v[212:215], v[20:23]
	v_mfma_f32_16x16x32_bf16 v[16:19], v[188:191], v[220:223], v[16:19]
	v_mfma_f32_16x16x32_bf16 v[12:15], v[196:199], v[212:215], v[12:15]
	v_mfma_f32_16x16x32_bf16 v[8:11], v[196:199], v[220:223], v[8:11]
	v_mfma_f32_16x16x32_bf16 v[4:7], v[204:207], v[212:215], v[4:7]
	v_mfma_f32_16x16x32_bf16 v[0:3], v[204:207], v[220:223], v[0:3]
	v_mfma_f32_16x16x32_bf16 v[28:31], v[154:157], v[216:219], v[28:31]
	v_mfma_f32_16x16x32_bf16 v[24:27], v[154:157], v[224:227], v[24:27]
	v_mfma_f32_16x16x32_bf16 v[20:23], v[192:195], v[216:219], v[20:23]
	v_mfma_f32_16x16x32_bf16 v[16:19], v[192:195], v[224:227], v[16:19]
	v_mfma_f32_16x16x32_bf16 v[12:15], v[200:203], v[216:219], v[12:15]
	v_mfma_f32_16x16x32_bf16 v[8:11], v[200:203], v[224:227], v[8:11]
	v_mfma_f32_16x16x32_bf16 v[4:7], v[208:211], v[216:219], v[4:7]
	v_mfma_f32_16x16x32_bf16 v[0:3], v[208:211], v[224:227], v[0:3]
	s_setprio 0
	s_barrier
; #define LDA(dst, b, h) for (int m = 0; m < 4; ++m) for (int k = 0; k < 2; ++k) \
;     dst[m][k] = *reinterpret_cast<const bf16x8*>((char*)SA(b, h) + lds_byte(wr * 64 + m * 16 + fr, k * 32 + fq * 8))
; #define LDB(dst, b, h) for (int n = 0; n < 2; ++n) for (int k = 0; k < 2; ++k) \
;     dst[n][k] = *reinterpret_cast<const bf16x8*>((char*)SB(b, h) + lds_byte(wc * 32 + n * 16 + fr, k * 32 + fq * 8))
; #define MMA(ai, bj, At, Bt_) do { __builtin_amdgcn_s_setprio(1); \
;     for (int m = 0; m < 4; ++m) for (int n = 0; n < 2; ++n) for (int k = 0; k < 2; ++k) \
;       acc[ai][bj][m][n] = __builtin_amdgcn_mfma_f32_16x16x32_bf16(At[m][k], Bt_[n][k], acc[ai][bj][m][n], 0, 0, 0); \
;     __builtin_amdgcn_s_setprio(0); } while (0)
; #define WAIT_V(n) asm volatile("s_waitcnt vmcnt(" #n ")" ::: "memory")
; #define WAIT_L(n) asm volatile("s_waitcnt lgkmcnt(" #n ")" ::: "memory")
; #define BAR __builtin_amdgcn_s_barrier()
; __device__ __forceinline__ void gemm_tile(const bf16_t* __restrict__ A, const bf16_t* __restrict__ Bt, int K, int brow, int bcol,
;                                           int mode, const Params& p, char* wsb, const float* xg, float* outg, int S, char* shmc) {
;     ...
;   { LDB(B0, 1, 0); LDA(At, 1, 0); WAIT_V(2); BAR; WAIT_L(0); MMA(0, 0, At, B0); BAR;
;     LDB(B1, 1, 1); WAIT_V(0); BAR; WAIT_L(0); MMA(0, 1, At, B1); BAR;
;     LDA(At, 1, 1); BAR; WAIT_L(0); MMA(1, 0, At, B0); MMA(1, 1, At, B1); BAR; }
;   if (wr == 0) BAR;
	ds_read_b128 v[188:191], v131
	ds_read_b128 v[192:195], v131 offset:1024
	ds_read_b128 v[196:199], v131 offset:2048
	ds_read_b128 v[200:203], v131 offset:3072
	ds_read_b128 v[136:139], v171 offset:32768
	ds_read_b128 v[204:207], v171 offset:33792
	ds_read_b128 v[208:211], v170 offset:32768
	ds_read_b128 v[212:215], v170 offset:33792
	ds_read_b128 v[216:219], v169 offset:32768
	ds_read_b128 v[220:223], v169 offset:33792
	ds_read_b128 v[224:227], v167 offset:32768
	ds_read_b128 v[228:231], v167 offset:33792
	s_waitcnt vmcnt(2)
	s_barrier
	s_waitcnt lgkmcnt(0)
	s_setprio 1
	s_waitcnt lgkmcnt(0)
	v_mfma_f32_16x16x32_bf16 v[124:127], v[136:139], v[188:191], v[124:127]
	v_mfma_f32_16x16x32_bf16 v[120:123], v[136:139], v[196:199], v[120:123]
	v_mfma_f32_16x16x32_bf16 v[116:119], v[208:211], v[188:191], v[116:119]
	v_mfma_f32_16x16x32_bf16 v[112:115], v[208:211], v[196:199], v[112:115]
	v_mfma_f32_16x16x32_bf16 v[108:111], v[216:219], v[188:191], v[108:111]
	v_mfma_f32_16x16x32_bf16 v[104:107], v[216:219], v[196:199], v[104:107]
	v_mfma_f32_16x16x32_bf16 v[100:103], v[224:227], v[188:191], v[100:103]
	v_mfma_f32_16x16x32_bf16 v[96:99], v[224:227], v[196:199], v[96:99]
	v_mfma_f32_16x16x32_bf16 v[152:155], v[204:207], v[192:195], v[124:127]
	v_mfma_f32_16x16x32_bf16 v[156:159], v[204:207], v[200:203], v[120:123]
	v_mfma_f32_16x16x32_bf16 v[144:147], v[212:215], v[192:195], v[116:119]
	v_mfma_f32_16x16x32_bf16 v[148:151], v[212:215], v[200:203], v[112:115]
	v_mfma_f32_16x16x32_bf16 v[132:135], v[220:223], v[192:195], v[108:111]
	v_mfma_f32_16x16x32_bf16 v[140:143], v[220:223], v[200:203], v[104:107]
	v_mfma_f32_16x16x32_bf16 v[116:119], v[228:231], v[192:195], v[100:103]
	v_mfma_f32_16x16x32_bf16 v[124:127], v[228:231], v[200:203], v[96:99]
	s_setprio 0
	s_barrier
	ds_read_b128 v[232:235], v130
	ds_read_b128 v[236:239], v130 offset:1024
	ds_read_b128 v[240:243], v130 offset:2048
	ds_read_b128 v[244:247], v130 offset:3072
	s_waitcnt vmcnt(0)
	s_barrier
	s_waitcnt lgkmcnt(0)
	s_setprio 1
	s_waitcnt lgkmcnt(0)
	v_mfma_f32_16x16x32_bf16 v[92:95], v[136:139], v[232:235], v[92:95]
	v_mfma_f32_16x16x32_bf16 v[88:91], v[136:139], v[240:243], v[88:91]
	v_mfma_f32_16x16x32_bf16 v[84:87], v[208:211], v[232:235], v[84:87]
	v_mfma_f32_16x16x32_bf16 v[80:83], v[208:211], v[240:243], v[80:83]
	v_mfma_f32_16x16x32_bf16 v[76:79], v[216:219], v[232:235], v[76:79]
	v_mfma_f32_16x16x32_bf16 v[72:75], v[216:219], v[240:243], v[72:75]
	v_mfma_f32_16x16x32_bf16 v[68:71], v[224:227], v[232:235], v[68:71]
	v_mfma_f32_16x16x32_bf16 v[64:67], v[224:227], v[240:243], v[64:67]
	v_mfma_f32_16x16x32_bf16 v[128:131], v[204:207], v[236:239], v[92:95]
	v_mfma_f32_16x16x32_bf16 v[136:139], v[204:207], v[244:247], v[88:91]
	v_mfma_f32_16x16x32_bf16 v[112:115], v[212:215], v[236:239], v[84:87]
	v_mfma_f32_16x16x32_bf16 v[120:123], v[212:215], v[244:247], v[80:83]
	v_mfma_f32_16x16x32_bf16 v[104:107], v[220:223], v[236:239], v[76:79]
	v_mfma_f32_16x16x32_bf16 v[108:111], v[220:223], v[244:247], v[72:75]
	v_mfma_f32_16x16x32_bf16 v[96:99], v[228:231], v[236:239], v[68:71]
	v_mfma_f32_16x16x32_bf16 v[100:103], v[228:231], v[244:247], v[64:67]
	s_setprio 0
	s_barrier
	ds_read_b128 v[204:207], v171 offset:49152
	ds_read_b128 v[208:211], v171 offset:50176
	ds_read_b128 v[212:215], v170 offset:49152
	ds_read_b128 v[170:173], v170 offset:50176
	ds_read_b128 v[216:219], v169 offset:49152
	ds_read_b128 v[220:223], v169 offset:50176
	ds_read_b128 v[224:227], v167 offset:49152
	ds_read_b128 v[228:231], v167 offset:50176
	s_barrier
	s_waitcnt lgkmcnt(0)
	s_setprio 1
	s_waitcnt lgkmcnt(0)
	v_mfma_f32_16x16x32_bf16 v[60:63], v[204:207], v[188:191], v[60:63]
	v_mfma_f32_16x16x32_bf16 v[56:59], v[204:207], v[196:199], v[56:59]
	v_mfma_f32_16x16x32_bf16 v[52:55], v[212:215], v[188:191], v[52:55]
	v_mfma_f32_16x16x32_bf16 v[48:51], v[212:215], v[196:199], v[48:51]
	v_mfma_f32_16x16x32_bf16 v[44:47], v[216:219], v[188:191], v[44:47]
	v_mfma_f32_16x16x32_bf16 v[40:43], v[216:219], v[196:199], v[40:43]
	v_mfma_f32_16x16x32_bf16 v[36:39], v[224:227], v[188:191], v[36:39]
	v_mfma_f32_16x16x32_bf16 v[32:35], v[224:227], v[196:199], v[32:35]
	v_mfma_f32_16x16x32_bf16 v[88:91], v[208:211], v[192:195], v[60:63]
	v_mfma_f32_16x16x32_bf16 v[92:95], v[208:211], v[200:203], v[56:59]
	v_mfma_f32_16x16x32_bf16 v[80:83], v[170:173], v[192:195], v[52:55]
	v_mfma_f32_16x16x32_bf16 v[84:87], v[170:173], v[200:203], v[48:51]
	v_mfma_f32_16x16x32_bf16 v[72:75], v[220:223], v[192:195], v[44:47]
	v_mfma_f32_16x16x32_bf16 v[76:79], v[220:223], v[200:203], v[40:43]
	v_mfma_f32_16x16x32_bf16 v[64:67], v[228:231], v[192:195], v[36:39]
	v_mfma_f32_16x16x32_bf16 v[68:71], v[228:231], v[200:203], v[32:35]
	s_setprio 0
	s_setprio 1
	v_mfma_f32_16x16x32_bf16 v[28:31], v[204:207], v[232:235], v[28:31]
	v_mfma_f32_16x16x32_bf16 v[24:27], v[204:207], v[240:243], v[24:27]
	v_mfma_f32_16x16x32_bf16 v[20:23], v[212:215], v[232:235], v[20:23]
	v_mfma_f32_16x16x32_bf16 v[16:19], v[212:215], v[240:243], v[16:19]
	v_mfma_f32_16x16x32_bf16 v[12:15], v[216:219], v[232:235], v[12:15]
	v_mfma_f32_16x16x32_bf16 v[8:11], v[216:219], v[240:243], v[8:11]
	v_mfma_f32_16x16x32_bf16 v[4:7], v[224:227], v[232:235], v[4:7]
	v_mfma_f32_16x16x32_bf16 v[0:3], v[224:227], v[240:243], v[0:3]
	v_mfma_f32_16x16x32_bf16 v[56:59], v[208:211], v[236:239], v[28:31]
	v_mfma_f32_16x16x32_bf16 v[60:63], v[208:211], v[244:247], v[24:27]
	v_mfma_f32_16x16x32_bf16 v[48:51], v[170:173], v[236:239], v[20:23]
	v_mfma_f32_16x16x32_bf16 v[52:55], v[170:173], v[244:247], v[16:19]
	v_mfma_f32_16x16x32_bf16 v[40:43], v[220:223], v[236:239], v[12:15]
	v_mfma_f32_16x16x32_bf16 v[44:47], v[220:223], v[244:247], v[8:11]
	v_mfma_f32_16x16x32_bf16 v[32:35], v[228:231], v[236:239], v[4:7]
	v_mfma_f32_16x16x32_bf16 v[36:39], v[228:231], v[244:247], v[0:3]
	s_setprio 0
	s_movk_i32 s4, 0x100
	v_cmp_gt_u32_e32 vcc, s4, v162
	s_barrier
	s_and_saveexec_b64 s[4:5], vcc
	s_cbranch_execz .LBB0_172
	s_barrier
